# conv tile slot per workgroup from an 8-entry table: first, between the two attention units, or after them (table 0x9944), spreading the conv tiles over the attention phase
# speedup vs baseline: 1.0109x; 1.0090x over previous
.LBB0_341:
	s_cmp_lt_i32 s26, 4
	s_cselect_b64 s[6:7], -1, 0
	s_and_b64 s[30:31], s[6:7], s[4:5]
	s_andn2_b64 vcc, exec, s[30:31]
	s_cbranch_vccnz .LBB0_509
	v_and_b32_e32 v2, 63, v0
	s_cmpk_gt_i32 s2, 0xff
	s_mov_b64 s[34:35], s[24:25]
	v_mov_b32_e32 v254, v2
	s_cbranch_scc1 .LBB0_383
	s_lshr_b32 s32, s2, 3
	s_and_b32 s32, s32, 7
	s_lshl_b32 s32, s32, 1
	s_lshr_b32 s32, 0x9944, s32
	s_and_b32 s32, s32, 3
	s_lshl_b32 s32, s32, 4
	s_cmp_lt_u32 s32, 16
	s_cbranch_scc1 .Lconv_entry
	s_mov_b32 s11, 0
	s_mov_b64 s[4:5], exec
	s_branch .LBB0_385

.LBB0_385:
	s_or_b64 exec, exec, s[4:5]
	s_and_b32 s98, s32, 15
	s_cmp_lg_u32 s98, 1
	s_cbranch_scc1 .Lst_norm
	s_add_i32 s32, s32, 1
	s_mov_b64 s[98:99], exec
	v_cmp_eq_u32_e64 s[100:101], 0, v0
	s_and_b64 exec, exec, s[100:101]
	s_cbranch_execz .Lst_rest
	s_waitcnt vmcnt(0)
	v_mov_b32_e32 v250, 0x6000
	v_mov_b32_e32 v251, 1
	global_atomic_add v250, v251, s[24:25]
.Lst_rest:
	s_mov_b64 exec, s[98:99]
	v_and_b32_e32 v254, 63, v0
	s_bitcmp1_b32 s32, 4
	s_cbranch_scc1 .Lst_norm
	s_and_b32 s66, s2, 7
	s_lshr_b32 s67, s2, 3
	s_mov_b64 s[8:9], -1
	s_branch .LBB0_476
.Lst_norm:
	s_ashr_i32 s6, s2, 31
	s_lshr_b32 s6, s6, 29
	s_add_i32 s6, s2, s6
	s_and_b32 s7, s6, -8
	s_ashr_i32 s5, s3, 3
	s_sub_i32 s66, s2, s7
	s_mul_i32 s5, s5, s66
	s_ashr_i32 s67, s6, 3
	s_and_b32 s4, s3, 7
	s_add_i32 s5, s5, s67
	s_cmpk_eq_i32 s3, 0x100
	s_cselect_b64 s[8:9], -1, 0
	s_cmpk_lg_i32 s3, 0x100
	s_mov_b64 s[14:15], s[24:25]
	s_cselect_b64 s[12:13], -1, 0
	s_add_u32 s68, s14, 0x5000000
	s_addc_u32 s69, s15, 0
	s_add_u32 s73, s14, 0x6000000
	s_addc_u32 s74, s15, 0
	s_add_u32 s75, s14, 0x7000000
	s_addc_u32 s76, s15, 0
	s_cmp_eq_u32 s4, 0
	s_cselect_b32 s77, s5, s2
	s_and_b32 s5, s77, 3
	s_and_b32 s6, s77, 2
	s_add_i32 s6, s6, s5
	s_and_b32 s4, s77, 4
	s_ashr_i32 s78, s77, 3
	s_sub_i32 s7, 13, s6
	s_xor_b32 s10, s5, 15
	s_sub_i32 s16, 13, s5
	s_add_i32 s17, s5, 2
	s_or_b32 s18, s5, 4
	s_cmp_lt_u32 s5, 2
	s_cselect_b32 s5, s10, s16
	s_cselect_b32 s10, s17, s18
	s_cmp_eq_u32 s4, 0
	s_cselect_b32 s79, s5, s7
	s_cselect_b32 s80, s10, s6
	v_mov_b32_e32 v223, 0
	s_mov_b64 s[16:17], 0x80
	s_mov_b64 s[18:19], 0x20000
	s_mov_b64 s[20:21], 0x40000
	s_mov_b64 s[22:23], 0x60000
	s_mov_b64 s[34:35], 0x20080
	s_mov_b64 s[36:37], 0x6080000
	s_mov_b64 s[38:39], 0x7040000
	s_mov_b64 s[40:41], 0x7040080
	s_mov_b32 s81, 0x41000000
	s_mov_b64 s[42:43], 0x60a0000
	s_mov_b64 s[44:45], 0x7060000
	s_mov_b64 s[46:47], 0x7060080
	s_mov_b64 s[48:49], 0x6060000
	s_mov_b64 s[50:51], 0x7020000
	s_mov_b64 s[52:53], 0x7020080
	s_mov_b32 s82, 0xb000000
	v_mov_b32_e32 v232, 0xff800000
	s_lshr_b32 s83, s32, 8
	v_mov_b32_e32 v178, v254
	s_branch .LBB0_388

.LBB0_387:
	s_and_b64 vcc, exec, s[4:5]
	s_mov_b32 s10, s85
	s_mov_b32 s54, s84
	s_cbranch_vccnz .LBB0_476
	s_cmp_lg_u32 s32, 16
	s_cbranch_scc1 .Lmid_skip
	s_mov_b32 s32, 0x111
	v_and_b32_e32 v2, 63, v0
	v_or_b32_e32 v194, 0x400, v0
	v_or_b32_e32 v195, 0x800, v0
	v_or_b32_e32 v211, 0xc00, v0
	v_and_b32_e32 v254, 63, v0
	s_mov_b64 s[34:35], s[24:25]
	s_branch .Lconv_entry
.Lmid_skip:
.LBB0_388:
	s_mov_b64 s[6:7], -1
	s_and_b64 vcc, exec, s[12:13]
	s_cbranch_vccz .LBB0_391
	s_mul_i32 s55, s83, s3
	s_add_i32 s55, s55, s77
	s_mov_b64 s[6:7], 0
	s_cmpk_gt_i32 s55, 0x1ff
	s_mov_b64 s[4:5], 0
	s_mov_b32 s84, s54
	s_mov_b32 s85, s10
	s_cbranch_scc1 .LBB0_391
	s_ashr_i32 s4, s55, 31
	s_lshr_b32 s4, s4, 28
	s_add_i32 s4, s55, s4
	s_ashr_i32 s84, s4, 4
	s_and_b32 s4, s4, -16
	s_sub_i32 s4, s4, s55
	s_add_i32 s85, s4, 15
	s_mov_b64 s[4:5], -1

.LBB0_396:
	s_cmp_ge_u32 s32, 16
	s_cbranch_scc1 .Lcv_skip
	s_cmp_lg_u32 s83, 1
	s_cbranch_scc1 .Lcv_skip
	s_mov_b64 s[98:99], exec
	v_cmp_eq_u32_e64 s[100:101], 0, v0
	s_and_b64 exec, exec, s[100:101]
	s_cbranch_execz .Lcv_rest
	v_mov_b32_e32 v250, 0x6000
	v_mov_b32_e32 v251, 1
	global_atomic_add v250, v251, s[24:25]

.LBB0_476:
	s_ashr_i32 s4, s3, 31
	s_lshr_b32 s4, s4, 29
	s_add_i32 s4, s3, s4
	v_lshlrev_b32_e32 v1, 6, v0
	s_ashr_i32 s4, s4, 3
	v_and_b32_e32 v149, 0x3c0, v1
	v_lshlrev_b32_e32 v1, 2, v0
	s_mul_i32 s20, s4, s66
	v_and_b32_e32 v147, 32, v1
	v_lshrrev_b32_e32 v1, 5, v0
	v_lshrrev_b32_e32 v3, 1, v0
	s_add_i32 s20, s20, s67
	v_and_b32_e32 v1, 4, v1
	v_bfe_u32 v2, v0, 2, 2
	v_and_b32_e32 v142, 24, v3
	s_and_b32 s22, s20, 3
	v_or3_b32 v1, v1, v2, v142
	v_lshlrev_b32_e32 v2, 4, v0
	s_bitcmp0_b32 s20, 2
	v_or_b32_e32 v145, 0x2000, v2
	s_cselect_b64 s[4:5], -1, 0
	v_lshrrev_b32_e32 v3, 7, v145
	s_movk_i32 s6, 0x60
	v_and_b32_e32 v4, 32, v0
	s_and_b64 s[4:5], s[8:9], s[4:5]
	v_and_or_b32 v150, v3, s6, v1
	v_bitop3_b32 v143, v2, v4, 48 bitop3:0x6c
	v_and_b32_e32 v144, 64, v0
	v_bfe_u32 v146, v0, 2, 4
	s_movk_i32 s6, 0x70
	v_lshrrev_b32_e32 v2, 3, v0
	v_and_b32_e32 v148, 15, v0
	v_or_b32_e32 v151, v143, v144
	v_and_or_b32 v152, v3, s6, v146
	v_and_or_b32 v153, v2, 32, v1
	v_and_or_b32 v154, v2, 48, v146
	s_mov_b64 s[6:7], s[24:25]
	s_andn2_b64 vcc, exec, s[4:5]
	s_mov_b64 s[4:5], -1
	s_cbranch_vccz .LBB0_494
	s_andn2_b64 vcc, exec, s[8:9]
	s_cbranch_vccnz .LBB0_493
	s_cmp_lg_u32 s32, 32
	s_cbranch_scc1 .Lb_cont
	s_mov_b32 s32, 33
	v_and_b32_e32 v2, 63, v0
	v_or_b32_e32 v194, 0x400, v0
	v_or_b32_e32 v195, 0x800, v0
	v_or_b32_e32 v211, 0xc00, v0
	v_and_b32_e32 v254, 63, v0
	s_mov_b64 s[34:35], s[24:25]
	s_branch .Lconv_entry

.LBB0_494:
	s_andn2_b64 vcc, exec, s[4:5]
	s_cbranch_vccnz .LBB0_509
	s_cmp_lg_u32 s32, 32
	s_cbranch_scc1 .La_cont
	s_mov_b32 s32, 33
	v_and_b32_e32 v2, 63, v0
	v_or_b32_e32 v194, 0x400, v0
	v_or_b32_e32 v195, 0x800, v0
	v_or_b32_e32 v211, 0xc00, v0
	v_and_b32_e32 v254, 63, v0
	s_mov_b64 s[34:35], s[24:25]
	s_branch .Lconv_entry
.La_cont:
	s_cmp_gt_u32 s29, 63
	s_cbranch_scc1 .LBB0_501
	s_add_u32 s4, s6, 0x6000
	s_addc_u32 s5, s7, 0
	v_mov_b32_e32 v1, 0x400000
	v_mov_b64_e32 v[2:3], s[4:5]
	s_branch .LBB0_498
